# v25 + next-block prefetch at the diff-attention component 1->2 boundary (prompt units): component 2's K0/V0/K1/Q/K2 issued in front of component 1's drain
# speedup vs baseline: 1.0068x; 1.0038x over previous
;   #define DMA_K(t,slot) glds16s(Kb+(long)(t)*KVBLK*kp,ksrc,(unsigned)__builtin_amdgcn_readfirstlane(kdst+(slot)))
;   #define DMA_V(t,slot) do{ glds16s(Vb+(long)(t)*KVBLK*vp,vsrc,(unsigned)__builtin_amdgcn_readfirstlane(vdst+(slot))); \
;       if(VH==2) glds16s(Vb+(long)(t)*KVBLK*vp+64,vsrc,(unsigned)__builtin_amdgcn_readfirstlane(vdst+(slot)+8192)); }while(0)
; template<int VH,bool HAS_BIAS,int MODE> __device__ __forceinline__ void attn_unit2(const bf16*Qb,int qp,const bf16*__restrict__ Kb,int kp,const bf16*__restrict__ Vb,int vp,bf16*Ob,int op,int q0,int NT,const float*relb,char*shm,float lam,const float*subg,float gmul){
;     ...
;   DMA_K(0,0);DMA_V(0,0);DMA_K(1,KSL);
;   bf16x8 qr[4];
;   #pragma unroll
;   for(int d0=0;d0<4;++d0)qr[d0]=*reinterpret_cast<const bf16x8*>(&Qw[(long)r32*qp+d0*16+hi*8]);
;   DMA_K(2,2*KSL);
; __global__ void __launch_bounds__(NWAVES * 64, 2) mega_fwd(Args args) {
;     ...
;                 attn_body::attn_unit2<2, true, 1>((const attn_body::bf16*)(Qb + tok0 * 1024 + (2 * h) * 64), 1024, (const attn_body::bf16*)(Kb + tok0 * 1024 + (2 * h) * 64), 1024,
;                     (const attn_body::bf16*)(Vb + tok0 * 1024 + h * 128), 1024, (attn_body::bf16*)(Ob + tok0 * 1024 + h * 128), 1024, qb * 256, NT, ap->in[10] + h, (char*)lds + RING_OFF, lam, ap->in[23], 1.0f - LAMBDA_INIT1);
;                 attn_body::attn_unit2<2, true, 2>((const attn_body::bf16*)(Qb + tok0 * 1024 + (2 * h + 1) * 64), 1024, (const attn_body::bf16*)(Kb + tok0 * 1024 + (2 * h + 1) * 64), 1024,
;                     (const attn_body::bf16*)(Vb + tok0 * 1024 + h * 128), 1024, (attn_body::bf16*)(Ob + tok0 * 1024 + h * 128), 1024, qb * 256, NT, ap->in[10] + h, (char*)lds + RING_OFF, lam, ap->in[23], 1.0f - LAMBDA_INIT1); }
.LBB0_1139:
	s_cmp_lg_u32 s69, 32
	s_cbranch_scc1 .Lnbp_none
	s_waitcnt lgkmcnt(0)
	s_barrier
	s_add_u32 s98, s44, 0x80
	s_addc_u32 s99, s45, 0
	s_mov_b32 m0, s33
	s_nop 0
	global_load_lds_dwordx4 v202, s[98:99]
	s_add_i32 m0, s33, 0x8000
	s_nop 0
	global_load_lds_dwordx4 v203, s[46:47]
	s_add_i32 m0, s33, 0xa000
	s_nop 0
	global_load_lds_dwordx4 v203, s[48:49]
	s_add_u32 s98, s44, 0x20080
	s_addc_u32 s99, s45, 0
	s_add_i32 m0, s33, 0x2000
	s_nop 0
	global_load_lds_dwordx4 v202, s[98:99]
	v_readfirstlane_b32 s98, v184
	s_nop 3
	s_ashr_i32 s98, s98, 6
	s_lshl_b32 s98, s98, 5
	s_add_i32 s98, s98, s77
	s_ashr_i32 s99, s98, 31
	s_lshl_b64 s[98:99], s[98:99], 11
	s_add_u32 s100, s75, s98
	s_addc_u32 s101, s76, s99
	v_and_b32_e32 v253, 31, v184
	v_bfe_u32 v254, v184, 5, 1
	v_lshlrev_b32_e32 v253, 11, v253
	v_lshl_or_b32 v253, v254, 4, v253
	global_load_dwordx4 v[158:161], v253, s[100:101] offset:128
	global_load_dwordx4 v[154:157], v253, s[100:101] offset:160
	global_load_dwordx4 v[150:153], v253, s[100:101] offset:192
	global_load_dwordx4 v[146:149], v253, s[100:101] offset:224
	s_add_u32 s98, s44, 0x40080
	s_addc_u32 s99, s45, 0
	s_add_i32 m0, s33, 0x4000
	s_nop 0
	global_load_lds_dwordx4 v202, s[98:99]

; #define WAIT_BAR(N) asm volatile("s_waitcnt vmcnt(" #N ") lgkmcnt(0)\n\ts_barrier":::"memory")
;   #define DMA_K(t,slot) glds16s(Kb+(long)(t)*KVBLK*kp,ksrc,(unsigned)__builtin_amdgcn_readfirstlane(kdst+(slot)))
;   #define DMA_V(t,slot) do{ glds16s(Vb+(long)(t)*KVBLK*vp,vsrc,(unsigned)__builtin_amdgcn_readfirstlane(vdst+(slot))); \
;       if(VH==2) glds16s(Vb+(long)(t)*KVBLK*vp+64,vsrc,(unsigned)__builtin_amdgcn_readfirstlane(vdst+(slot)+8192)); }while(0)
;   #define BIASADD(P0,P1,t) do{ if(HAS_BIAS&&(t)>=tn0&&(t)<tn1){ const lds_f32*bp_=btab+(64*(t)+lanebias); \
;     _Pragma("unroll") for(int r=0;r<16;++r){ P0[r]+=bp_[(r&3)+8*(r>>2)]; P1[r]+=bp_[(r&3)+8*(r>>2)+32]; } } }while(0)
; template<int VH,bool HAS_BIAS,int MODE> __device__ __forceinline__ void attn_unit2(const bf16*Qb,int qp,const bf16*__restrict__ Kb,int kp,const bf16*__restrict__ Vb,int vp,bf16*Ob,int op,int q0,int NT,const float*relb,char*shm,float lam,const float*subg,float gmul){
;     ...
;   DMA_K(0,0);DMA_V(0,0);DMA_K(1,KSL);
;   bf16x8 qr[4];
;   #pragma unroll
;   for(int d0=0;d0<4;++d0)qr[d0]=*reinterpret_cast<const bf16x8*>(&Qw[(long)r32*qp+d0*16+hi*8]);
;   DMA_K(2,2*KSL);
;   float l_reg=0.f;f32x16 o[2*VH];
;   #pragma unroll
;   for(int d_=0;d_<2*VH;++d_)o[d_]=f32x16{};
;   const f32x16 zero16=f32x16{};
;   f32x16 pA0,pA1,pB0,pB1; bf16x8 kf[4];
;   int sv_prev=0,sv_cur=0,sv_next=VSL;
;     ...
;   if(VH==1){WAIT_BAR(3);}else{WAIT_BAR(4);}
;   qkt(pA0,pA1,shm+LM::L_K,qr,zero16,r32,hi);
;   BIASADD(pA0,pA1,0);
;   _Pragma("unroll") for(int r=0;r<16;++r){pA0[r]=__builtin_amdgcn_exp2f(pA0[r]);pA1[r]=__builtin_amdgcn_exp2f(pA1[r]);}
.LBB0_1153:
	s_or_b64 exec, exec, s[54:55]
	s_add_u32 s8, s44, 0x80
	s_addc_u32 s9, s45, 0
	s_ashr_i32 s54, s81, 6
	s_lshl_b32 s6, s54, 5
	s_add_i32 s6, s6, s77
	s_ashr_i32 s7, s6, 31
	s_lshl_b64 s[10:11], s[6:7], 11
	s_add_u32 s12, s75, s10
	v_and_b32_e32 v197, 63, v184
	s_addc_u32 s13, s76, s11
	s_lshl_b32 s7, s54, 4
	v_bfe_u32 v2, v184, 2, 4
	v_lshl_add_u32 v206, v197, 11, s7
	v_and_or_b32 v2, s7, 48, v2
	s_ashr_i32 s7, s81, 3
	s_and_b32 s7, s7, 0x7fffffe0
	v_lshl_add_u32 v2, v2, 10, s7
	s_lshl_b32 s7, s54, 10
	s_cmp_lg_u32 0, -1
	s_cselect_b32 s14, 0, 0
	s_add_i32 s33, s7, s14
	s_add_i32 s14, s6, 0xffffffa6
	s_add_i32 s57, s33, 0x8000
	s_ashr_i32 s14, s14, 6
	v_lshlrev_b32_e32 v3, 3, v184
	s_cmpk_gt_i32 s6, 0x59
	v_and_b32_e32 v199, 24, v3
	s_cselect_b32 s55, s14, 0
	s_add_i32 s14, s6, 0xb9
	v_or_b32_e32 v2, v2, v199
	s_ashr_i32 s56, s14, 6
	v_lshlrev_b32_e32 v207, 1, v2
	v_and_b32_e32 v185, 31, v184
	s_add_i32 s14, s33, 0xa000
	v_bfe_u32 v35, v184, 5, 1
	s_add_u32 s40, s44, 0x20080
	v_lshlrev_b32_e32 v2, 11, v185
	s_addc_u32 s41, s45, 0
	s_add_i32 s14, s33, 0x2000
	v_lshl_or_b32 v2, v35, 4, v2
	s_add_u32 s12, s44, 0x40080
	v_lshlrev_b32_e32 v194, 10, v35
	v_lshlrev_b32_e32 v2, 4, v185
	s_addc_u32 s13, s45, 0
	s_add_i32 s14, s33, 0x4000
	v_add3_u32 v205, 0, v194, v2
	s_cmp_eq_u32 s69, 32
	s_cbranch_scc1 .Lnbp_have
	s_add_u32 s98, s44, 0x80
	s_addc_u32 s99, s45, 0
	s_mov_b32 m0, s33
	s_nop 0
	global_load_lds_dwordx4 v206, s[98:99]
	s_add_i32 m0, s33, 0x8000
	s_nop 0
	global_load_lds_dwordx4 v207, s[46:47]
	s_add_i32 m0, s33, 0xa000
	s_nop 0
	global_load_lds_dwordx4 v207, s[48:49]
	s_add_u32 s98, s44, 0x20080
	s_addc_u32 s99, s45, 0
	s_add_i32 m0, s33, 0x2000
	s_nop 0
	global_load_lds_dwordx4 v206, s[98:99]
	v_readfirstlane_b32 s98, v184
	s_nop 3
	s_ashr_i32 s98, s98, 6
	s_lshl_b32 s98, s98, 5
	s_add_i32 s98, s98, s77
	s_ashr_i32 s99, s98, 31
	s_lshl_b64 s[98:99], s[98:99], 11
	s_add_u32 s100, s75, s98
	s_addc_u32 s101, s76, s99
	v_and_b32_e32 v253, 31, v184
	v_bfe_u32 v254, v184, 5, 1
	v_lshlrev_b32_e32 v253, 11, v253
	v_lshl_or_b32 v253, v254, 4, v253
	global_load_dwordx4 v[158:161], v253, s[100:101] offset:128
	global_load_dwordx4 v[154:157], v253, s[100:101] offset:160
	global_load_dwordx4 v[150:153], v253, s[100:101] offset:192
	global_load_dwordx4 v[146:149], v253, s[100:101] offset:224
	s_add_u32 s98, s44, 0x40080
	s_addc_u32 s99, s45, 0
	s_add_i32 m0, s33, 0x4000
	s_nop 0
	global_load_lds_dwordx4 v206, s[98:99]
.Lnbp_have:
	s_waitcnt vmcnt(4) lgkmcnt(0)
	s_barrier
	ds_read_b128 v[2:5], v205
	ds_read_b128 v[18:21], v205 offset:512
	ds_read_b128 v[36:39], v205 offset:2048
	s_cmp_lt_i32 s55, 1
	s_cselect_b64 s[12:13], -1, 0
	s_cmp_gt_i32 s56, 0
	s_cselect_b64 s[40:41], -1, 0
	s_and_b64 s[12:13], s[12:13], s[40:41]
	v_lshlrev_b32_e32 v198, 2, v35
	v_or_b32_e32 v204, s6, v185
	s_and_b64 vcc, exec, s[12:13]
	s_waitcnt vmcnt(3) lgkmcnt(0)
	v_mfma_f32_32x32x16_bf16 v[2:17], v[2:5], v[158:161], 0
	s_waitcnt vmcnt(2)
	v_mfma_f32_32x32x16_bf16 v[2:17], v[36:39], v[154:157], v[2:17]
	ds_read_b128 v[36:39], v205 offset:2560
	v_mfma_f32_32x32x16_bf16 v[18:33], v[18:21], v[158:161], 0
	s_waitcnt lgkmcnt(0)
	v_mfma_f32_32x32x16_bf16 v[18:33], v[36:39], v[154:157], v[18:33]
	ds_read_b128 v[36:39], v205 offset:4096
	s_waitcnt vmcnt(1) lgkmcnt(0)
	v_mfma_f32_32x32x16_bf16 v[2:17], v[36:39], v[150:153], v[2:17]
	ds_read_b128 v[36:39], v205 offset:4608
	s_waitcnt lgkmcnt(0)
	v_mfma_f32_32x32x16_bf16 v[18:33], v[36:39], v[150:153], v[18:33]
	ds_read_b128 v[36:39], v205 offset:6144
	s_waitcnt vmcnt(0) lgkmcnt(0)
	v_mfma_f32_32x32x16_bf16 v[2:17], v[36:39], v[146:149], v[2:17]
	ds_read_b128 v[36:39], v205 offset:6656
	s_waitcnt lgkmcnt(0)
	v_mfma_f32_32x32x16_bf16 v[18:33], v[36:39], v[146:149], v[18:33]
	s_cbranch_vccz .LBB0_1155
	v_or_b32_e32 v36, 0x180, v198
	v_sub_u32_e32 v36, v36, v204
	v_lshl_add_u32 v36, v36, 2, 0
	v_add_u32_e32 v60, 0x14800, v36
	ds_read2_b32 v[36:37], v60 offset1:1
	ds_read2_b32 v[38:39], v60 offset0:2 offset1:3
	ds_read2_b32 v[40:41], v60 offset0:8 offset1:9
	ds_read2_b32 v[42:43], v60 offset0:10 offset1:11
	ds_read2_b32 v[44:45], v60 offset0:16 offset1:17
	ds_read2_b32 v[46:47], v60 offset0:18 offset1:19
	ds_read2_b32 v[48:49], v60 offset0:24 offset1:25
	ds_read2_b32 v[50:51], v60 offset0:26 offset1:27
	ds_read2_b32 v[52:53], v60 offset0:32 offset1:33
	ds_read2_b32 v[54:55], v60 offset0:34 offset1:35
	ds_read2_b32 v[56:57], v60 offset0:40 offset1:41
	ds_read2_b32 v[58:59], v60 offset0:42 offset1:43
	s_waitcnt lgkmcnt(4)
	v_pk_add_f32 v[16:17], v[16:17], v[50:51]
	v_pk_add_f32 v[14:15], v[14:15], v[48:49]
	v_pk_add_f32 v[12:13], v[12:13], v[46:47]
	v_pk_add_f32 v[10:11], v[10:11], v[44:45]
	ds_read2_b32 v[44:45], v60 offset0:48 offset1:49
	ds_read2_b32 v[46:47], v60 offset0:50 offset1:51
	ds_read2_b32 v[48:49], v60 offset0:56 offset1:57
	ds_read2_b32 v[50:51], v60 offset0:58 offset1:59
	v_pk_add_f32 v[8:9], v[8:9], v[42:43]
	v_pk_add_f32 v[6:7], v[6:7], v[40:41]
	v_pk_add_f32 v[4:5], v[4:5], v[38:39]
	v_pk_add_f32 v[2:3], v[2:3], v[36:37]
	s_waitcnt lgkmcnt(0)
	v_pk_add_f32 v[32:33], v[32:33], v[50:51]
	v_pk_add_f32 v[30:31], v[30:31], v[48:49]
	v_pk_add_f32 v[28:29], v[28:29], v[46:47]
	v_pk_add_f32 v[26:27], v[26:27], v[44:45]
	v_pk_add_f32 v[24:25], v[24:25], v[58:59]
	v_pk_add_f32 v[22:23], v[22:23], v[56:57]
	v_pk_add_f32 v[20:21], v[20:21], v[54:55]
	v_pk_add_f32 v[18:19], v[18:19], v[52:53]
